# hazard fix in step-array build (vcc to cndmask distance), otherwise as previous
# baseline (speedup 1.0000x reference)
; __device__ __forceinline__ float bf_lo(unsigned u) { return __uint_as_float(u << 16); }
; __device__ __forceinline__ float bf_hi(unsigned u) { return __uint_as_float(u & 0xffff0000u); }
; __device__ __forceinline__ float bf1(bf16_t u) { return __uint_as_float(((unsigned)u) << 16); }
; __device__ __forceinline__ float sigm(float x) { return rcpf_(1.f + ex2(-1.44269504f * x)); }
; __device__ __forceinline__ bf16x8 pack_p(const float* p) { u32x4 w; w.x = cvt_pk_bf16(p[0], p[1]); w.y = cvt_pk_bf16(p[2], p[3]); w.z = cvt_pk_bf16(p[4], p[5]); w.w = cvt_pk_bf16(p[6], p[7]); return __builtin_bit_cast(bf16x8, w); }
; __device__ __forceinline__ void nsa_tile(const Ctx& C, int b, int g, int t0) {
;     ...
;         const int tq = t0 + qi4;
;         bf16x8 q16f[2][2]; float gs4[2];
; #pragma unroll
;         for (int sub = 0; sub < 2; ++sub) {
;             const size_t tok4 = (size_t)b * S_ + tq + 4 * sub;
;             const bf16_t* qp = P + tok4 * PP + PC_Q + head4 * 64;
;             q16f[sub][1] = scale_q(*(const u32x4*)(qp + 32 + 8 * fq), QS);
;             const u32x4 mv4 = *(const u32x4*)(qp + 8 * fq), pv4 = *(const u32x4*)(qp + 8 * ((fq ^ 1) & 1));
;             const float* rt = (const float*)(C.ws + WS_ROPE) + tok4 * 16;
;             const f32x4 ca = *(const f32x4*)rt, cb2 = *(const f32x4*)(rt + 4), sa = *(const f32x4*)(rt + 8), sb = *(const f32x4*)(rt + 12);
;             const float cs[8] = {ca.x, ca.y, ca.z, ca.w, cb2.x, cb2.y, cb2.z, cb2.w}, sn[8] = {sa.x, sa.y, sa.z, sa.w, sb.x, sb.y, sb.z, sb.w};
;             const float mv[8] = {bf_lo(mv4.x), bf_hi(mv4.x), bf_lo(mv4.y), bf_hi(mv4.y), bf_lo(mv4.z), bf_hi(mv4.z), bf_lo(mv4.w), bf_hi(mv4.w)};
;             const float pp[8] = {bf_lo(pv4.x), bf_hi(pv4.x), bf_lo(pv4.y), bf_hi(pv4.y), bf_lo(pv4.z), bf_hi(pv4.z), bf_lo(pv4.w), bf_hi(pv4.w)};
;             const bool roped = fq < 2; const float sg = (fq == 0) ? -1.f : 1.f; float o[8];
; #pragma unroll
;             for (int e = 0; e < 8; ++e) o[e] = (roped ? (mv[e] * cs[e] + sg * pp[e] * sn[e]) : mv[e]) * QS;
;             q16f[sub][0] = pack_p(o);
;             gs4[sub] = sigm(bf1(P[tok4 * PP + PC_NG + head4 * 3 + 1]));
.LBB0_809:
	s_or_b64 exec, exec, s[0:1]
	v_bfe_u32 v12, v224, 2, 2
	v_or_b32_e32 v211, s97, v12
	v_or_b32_e32 v10, s76, v211
	v_mov_b64_e32 v[2:3], s[86:87]
	v_mad_u64_u32 v[4:5], s[0:1], v10, s67, v[2:3]
	v_mov_b32_e32 v179, v1
	v_lshl_add_u64 v[6:7], v[4:5], 0, v[178:179]
	s_bcnt1_i32_b64 s2, vcc
	v_add_co_u32_e32 v6, vcc, 0x1000, v6
	s_waitcnt lgkmcnt(0)
	s_add_i32 s3, s3, s2
	s_nop 0
	v_addc_co_u32_e32 v7, vcc, 0, v7, vcc
	global_load_ushort v251, v[6:7], off offset:2562
	v_or_b32_e32 v6, 4, v10
	v_mad_u64_u32 v[2:3], s[0:1], v6, s67, v[2:3]
	v_lshl_add_u64 v[8:9], v[2:3], 0, v[178:179]
	v_add_co_u32_e32 v8, vcc, 0x1000, v8
	v_mov_b64_e32 v[246:247], 0x200
	s_nop 0
	v_addc_co_u32_e32 v9, vcc, 0, v9, vcc
	global_load_ushort v210, v[8:9], off offset:2562
	v_mov_b64_e32 v[216:217], 0xaff
	v_ashrrev_i32_e32 v245, 4, v224
	s_cmp_eq_u32 s3, 0
	v_lshlrev_b64 v[228:229], 4, v[224:225]
	v_lshlrev_b32_e32 v226, 1, v186
	s_cbranch_scc1 .LBB0_865
	v_lshlrev_b32_e32 v232, 3, v245
	v_ashrrev_i32_e32 v233, 31, v232
	v_mov_b32_e32 v227, v1
	v_lshl_add_u64 v[18:19], v[4:5], 0, v[226:227]
	v_lshlrev_b64 v[4:5], 1, v[232:233]
	v_lshl_add_u64 v[8:9], v[18:19], 0, v[4:5]
	global_load_dwordx4 v[14:17], v[8:9], off offset:3136
	v_bitop3_b32 v13, v232, 8, v232 bitop3:0xc
	v_mov_b32_e32 v11, v1
	v_lshlrev_b64 v[10:11], 6, v[10:11]
	v_lshl_add_u64 v[10:11], s[78:79], 0, v[10:11]
	s_lshl_b64 s[0:1], s[22:23], 4
	s_add_u32 s10, s90, s0
	s_addc_u32 s11, s91, s1
	s_add_u32 s4, s94, s0
	s_addc_u32 s5, s95, s1
	v_cmp_gt_u32_e64 s[0:1], 16, v224
	v_cmp_gt_i32_e32 vcc, 2, v245
	v_mov_b32_e32 v7, v1
	v_lshlrev_b64 v[6:7], 6, v[6:7]
	v_lshl_add_u64 v[6:7], s[78:79], 0, v[6:7]
	v_lshl_add_u64 v[234:235], s[4:5], 0, v[228:229]
	v_lshl_add_u64 v[230:231], s[10:11], 0, v[228:229]
	s_lshl_b32 s3, s3, 1
	s_mov_b32 s2, 4
	s_add_i32 s18, s3, -1
	s_waitcnt vmcnt(0)
	v_lshlrev_b32_e32 v20, 16, v14
	v_and_b32_e32 v21, 0xffff0000, v14
	v_lshlrev_b32_e32 v14, 16, v15
	v_and_b32_e32 v15, 0xffff0000, v15
	v_pk_mul_f32 v[14:15], v[14:15], s[38:39] op_sel_hi:[1,0]
	v_pk_mul_f32 v[20:21], v[20:21], s[38:39] op_sel_hi:[1,0]
	v_cvt_pk_bf16_f32 v99, v14, v15
	v_lshlrev_b32_e32 v14, 16, v16
	v_and_b32_e32 v15, 0xffff0000, v16
	v_pk_mul_f32 v[14:15], v[14:15], s[38:39] op_sel_hi:[1,0]
	v_cvt_pk_bf16_f32 v98, v20, v21
	v_cvt_pk_bf16_f32 v100, v14, v15
	v_lshlrev_b32_e32 v14, 16, v17
	v_and_b32_e32 v15, 0xffff0000, v17
	v_pk_mul_f32 v[14:15], v[14:15], s[38:39] op_sel_hi:[1,0]
	s_nop 0
	v_cvt_pk_bf16_f32 v101, v14, v15
	global_load_dwordx4 v[14:17], v[8:9], off offset:3072
	v_lshlrev_b32_e32 v8, 1, v13
	v_mov_b32_e32 v9, v1
	v_lshl_add_u64 v[18:19], v[18:19], 0, v[8:9]
	global_load_dwordx4 v[18:21], v[18:19], off offset:3072
	s_nop 0
	global_load_dwordx4 v[22:25], v[10:11], off offset:16
	global_load_dwordx4 v[26:29], v[10:11], off offset:48
	global_load_dwordx4 v[30:33], v[10:11], off
	global_load_dwordx4 v[34:37], v[10:11], off offset:32
	s_waitcnt vmcnt(5)
	v_lshlrev_b32_e32 v10, 16, v14
	v_lshlrev_b32_e32 v44, 16, v17
	v_and_b32_e32 v46, 0xffff0000, v17
	v_and_b32_e32 v14, 0xffff0000, v14
	s_waitcnt vmcnt(4)
	v_lshlrev_b32_e32 v11, 16, v18
	v_and_b32_e32 v13, 0xffff0000, v18
	v_lshlrev_b32_e32 v17, 16, v19
	v_and_b32_e32 v41, 0xffff0000, v19
	v_cndmask_b32_e64 v11, v11, -v11, s[0:1]
	s_waitcnt vmcnt(1)
	v_mov_b32_e32 v18, v30
	s_waitcnt vmcnt(0)
	v_mov_b32_e32 v19, v34
	v_pk_mul_f32 v[18:19], v[18:19], v[10:11]
	v_lshlrev_b32_e32 v38, 16, v15
	v_add_f32_e32 v11, v18, v19
	v_and_b32_e32 v40, 0xffff0000, v15
	v_cndmask_b32_e32 v10, v10, v11, vcc
	v_cndmask_b32_e64 v15, v13, -v13, s[0:1]
	v_mov_b32_e32 v34, v31
	v_mul_f32_e32 v18, 0x3e38aa3b, v10
	v_pk_mul_f32 v[10:11], v[34:35], v[14:15]
	v_cndmask_b32_e64 v39, v17, -v17, s[0:1]
	v_add_f32_e32 v10, v10, v11
	v_cndmask_b32_e32 v10, v14, v10, vcc
	v_mul_f32_e32 v13, 0x3e38aa3b, v10
	v_mov_b32_e32 v10, v32
	v_mov_b32_e32 v11, v36
	v_pk_mul_f32 v[10:11], v[10:11], v[38:39]
	v_cndmask_b32_e64 v41, v41, -v41, s[0:1]
	v_add_f32_e32 v10, v10, v11
	v_cndmask_b32_e32 v10, v38, v10, vcc
	v_mov_b32_e32 v36, v33
	v_mul_f32_e32 v14, 0x3e38aa3b, v10
	v_pk_mul_f32 v[10:11], v[36:37], v[40:41]
	v_lshlrev_b32_e32 v43, 16, v20
	v_add_f32_e32 v10, v10, v11
	v_cndmask_b32_e32 v10, v40, v10, vcc
	v_lshlrev_b32_e32 v42, 16, v16
	v_mul_f32_e32 v15, 0x3e38aa3b, v10
	v_cndmask_b32_e64 v43, v43, -v43, s[0:1]
	v_mov_b32_e32 v10, v22
	v_mov_b32_e32 v11, v26
	v_pk_mul_f32 v[10:11], v[10:11], v[42:43]
	v_and_b32_e32 v20, 0xffff0000, v20
	v_add_f32_e32 v10, v10, v11
	v_and_b32_e32 v16, 0xffff0000, v16
	v_cndmask_b32_e32 v10, v42, v10, vcc
	v_cndmask_b32_e64 v17, v20, -v20, s[0:1]
	v_mov_b32_e32 v26, v23
	v_mul_f32_e32 v19, 0x3e38aa3b, v10
	v_pk_mul_f32 v[10:11], v[26:27], v[16:17]
	v_lshlrev_b32_e32 v45, 16, v21
	v_add_f32_e32 v10, v10, v11
	v_cndmask_b32_e32 v10, v16, v10, vcc
	v_mul_f32_e32 v16, 0x3e38aa3b, v10
	v_cndmask_b32_e64 v45, v45, -v45, s[0:1]
	v_mov_b32_e32 v10, v24
	v_mov_b32_e32 v11, v28
	v_pk_mul_f32 v[10:11], v[10:11], v[44:45]
	v_and_b32_e32 v21, 0xffff0000, v21
	v_add_f32_e32 v10, v10, v11
	v_cndmask_b32_e32 v10, v44, v10, vcc
	v_cndmask_b32_e64 v47, v21, -v21, s[0:1]
	v_mov_b32_e32 v28, v25
	v_mul_f32_e32 v17, 0x3e38aa3b, v10
	v_pk_mul_f32 v[10:11], v[28:29], v[46:47]
	v_cvt_pk_bf16_f32 v103, v14, v15
	v_add_f32_e32 v10, v10, v11
	v_cndmask_b32_e32 v10, v46, v10, vcc
	v_mul_f32_e32 v10, 0x3e38aa3b, v10
	v_cvt_pk_bf16_f32 v105, v17, v10
	v_lshl_add_u64 v[10:11], v[2:3], 0, v[226:227]
	v_lshl_add_u64 v[14:15], v[10:11], 0, v[4:5]
	global_load_dwordx4 v[2:5], v[14:15], off offset:3136
	v_cvt_pk_bf16_f32 v104, v19, v16
	v_lshl_add_u64 v[8:9], v[10:11], 0, v[8:9]
	v_cvt_pk_bf16_f32 v102, v18, v13
	global_load_dwordx4 v[8:11], v[8:9], off offset:3072
	s_waitcnt vmcnt(1)
; #define LAS __attribute__((address_space(3)))
; __device__ __forceinline__ float bf_lo(unsigned u) { return __uint_as_float(u << 16); }
; __device__ __forceinline__ float bf_hi(unsigned u) { return __uint_as_float(u & 0xffff0000u); }
; __device__ __forceinline__ float bf1(bf16_t u) { return __uint_as_float(((unsigned)u) << 16); }
; __device__ __forceinline__ float sigm(float x) { return rcpf_(1.f + ex2(-1.44269504f * x)); }
; __device__ __forceinline__ bf16x8 pack_p(const float* p) { u32x4 w; w.x = cvt_pk_bf16(p[0], p[1]); w.y = cvt_pk_bf16(p[2], p[3]); w.z = cvt_pk_bf16(p[4], p[5]); w.w = cvt_pk_bf16(p[6], p[7]); return __builtin_bit_cast(bf16x8, w); }
; __device__ __forceinline__ unsigned flash16_entry(int s, const LAS unsigned* list) {
;     const unsigned e = (unsigned)__builtin_amdgcn_readfirstlane((int)list[s >> 1]);
;     return (e & 0xffff0000u) | (2u * (e & 0xffffu) + (unsigned)(s & 1));
; }
; __device__ __forceinline__ void nsa_tile(const Ctx& C, int b, int g, int t0) {
;     ...
;         for (int sub = 0; sub < 2; ++sub) {
;             const size_t tok4 = (size_t)b * S_ + tq + 4 * sub;
;             const bf16_t* qp = P + tok4 * PP + PC_Q + head4 * 64;
;             q16f[sub][1] = scale_q(*(const u32x4*)(qp + 32 + 8 * fq), QS);
;             const u32x4 mv4 = *(const u32x4*)(qp + 8 * fq), pv4 = *(const u32x4*)(qp + 8 * ((fq ^ 1) & 1));
;             const float* rt = (const float*)(C.ws + WS_ROPE) + tok4 * 16;
;             const f32x4 ca = *(const f32x4*)rt, cb2 = *(const f32x4*)(rt + 4), sa = *(const f32x4*)(rt + 8), sb = *(const f32x4*)(rt + 12);
;             const float cs[8] = {ca.x, ca.y, ca.z, ca.w, cb2.x, cb2.y, cb2.z, cb2.w}, sn[8] = {sa.x, sa.y, sa.z, sa.w, sb.x, sb.y, sb.z, sb.w};
;             const float mv[8] = {bf_lo(mv4.x), bf_hi(mv4.x), bf_lo(mv4.y), bf_hi(mv4.y), bf_lo(mv4.z), bf_hi(mv4.z), bf_lo(mv4.w), bf_hi(mv4.w)};
;             const float pp[8] = {bf_lo(pv4.x), bf_hi(pv4.x), bf_lo(pv4.y), bf_hi(pv4.y), bf_lo(pv4.z), bf_hi(pv4.z), bf_lo(pv4.w), bf_hi(pv4.w)};
;             const bool roped = fq < 2; const float sg = (fq == 0) ? -1.f : 1.f; float o[8];
; #pragma unroll
;             for (int e = 0; e < 8; ++e) o[e] = (roped ? (mv[e] * cs[e] + sg * pp[e] * sn[e]) : mv[e]) * QS;
;             q16f[sub][0] = pack_p(o);
;             gs4[sub] = sigm(bf1(P[tok4 * PP + PC_NG + head4 * 3 + 1]));
;         }
	v_lshlrev_b32_e32 v16, 16, v2
	v_and_b32_e32 v17, 0xffff0000, v2
	v_lshlrev_b32_e32 v2, 16, v3
	v_and_b32_e32 v3, 0xffff0000, v3
	v_pk_mul_f32 v[2:3], v[2:3], s[38:39] op_sel_hi:[1,0]
	v_pk_mul_f32 v[16:17], v[16:17], s[38:39] op_sel_hi:[1,0]
	v_cvt_pk_bf16_f32 v107, v2, v3
	v_lshlrev_b32_e32 v2, 16, v4
	v_and_b32_e32 v3, 0xffff0000, v4
	v_pk_mul_f32 v[2:3], v[2:3], s[38:39] op_sel_hi:[1,0]
	v_cvt_pk_bf16_f32 v106, v16, v17
	v_cvt_pk_bf16_f32 v108, v2, v3
	v_lshlrev_b32_e32 v2, 16, v5
	v_and_b32_e32 v3, 0xffff0000, v5
	v_pk_mul_f32 v[2:3], v[2:3], s[38:39] op_sel_hi:[1,0]
	s_waitcnt vmcnt(0)
	v_and_b32_e32 v13, 0xffff0000, v9
	v_cvt_pk_bf16_f32 v109, v2, v3
	global_load_dwordx4 v[2:5], v[14:15], off offset:3072
	s_nop 0
	global_load_dwordx4 v[14:17], v[6:7], off offset:16
	global_load_dwordx4 v[18:21], v[6:7], off offset:48
	global_load_dwordx4 v[22:25], v[6:7], off
	global_load_dwordx4 v[26:29], v[6:7], off offset:32
	v_lshlrev_b32_e32 v7, 16, v8
	v_lshlrev_b32_e32 v35, 16, v10
	v_and_b32_e32 v10, 0xffff0000, v10
	v_lshlrev_b32_e32 v37, 16, v11
	v_and_b32_e32 v11, 0xffff0000, v11
	v_cndmask_b32_e64 v7, v7, -v7, s[0:1]
	v_cndmask_b32_e64 v33, v13, -v13, s[0:1]
	v_cndmask_b32_e64 v35, v35, -v35, s[0:1]
	v_cndmask_b32_e64 v37, v37, -v37, s[0:1]
	v_cndmask_b32_e64 v39, v11, -v11, s[0:1]
	s_waitcnt vmcnt(4)
	v_lshlrev_b32_e32 v6, 16, v2
	v_lshlrev_b32_e32 v30, 16, v3
	v_and_b32_e32 v32, 0xffff0000, v3
	v_lshlrev_b32_e32 v36, 16, v5
	v_and_b32_e32 v38, 0xffff0000, v5
	v_and_b32_e32 v3, 0xffff0000, v8
	v_lshlrev_b32_e32 v5, 16, v9
	s_waitcnt vmcnt(1)
	v_mov_b32_e32 v8, v22
	s_waitcnt vmcnt(0)
	v_mov_b32_e32 v9, v26
	v_pk_mul_f32 v[8:9], v[8:9], v[6:7]
	v_and_b32_e32 v2, 0xffff0000, v2
	v_add_f32_e32 v7, v8, v9
	v_cndmask_b32_e32 v6, v6, v7, vcc
	v_cndmask_b32_e64 v3, v3, -v3, s[0:1]
	v_mov_b32_e32 v26, v23
	v_mul_f32_e32 v8, 0x3e38aa3b, v6
	v_pk_mul_f32 v[6:7], v[26:27], v[2:3]
	v_cndmask_b32_e64 v31, v5, -v5, s[0:1]
	v_add_f32_e32 v3, v6, v7
	v_cndmask_b32_e32 v2, v2, v3, vcc
	v_mul_f32_e32 v6, 0x3e38aa3b, v2
	v_mov_b32_e32 v2, v24
	v_mov_b32_e32 v3, v28
	v_pk_mul_f32 v[2:3], v[2:3], v[30:31]
	v_mov_b32_e32 v28, v25
	v_add_f32_e32 v2, v2, v3
	v_cndmask_b32_e32 v2, v30, v2, vcc
	v_mul_f32_e32 v7, 0x3e38aa3b, v2
	v_pk_mul_f32 v[2:3], v[28:29], v[32:33]
	v_lshlrev_b32_e32 v34, 16, v4
	v_add_f32_e32 v2, v2, v3
	v_cndmask_b32_e32 v2, v32, v2, vcc
	v_mul_f32_e32 v9, 0x3e38aa3b, v2
	v_mov_b32_e32 v2, v14
	v_mov_b32_e32 v3, v18
	v_pk_mul_f32 v[2:3], v[2:3], v[34:35]
	v_and_b32_e32 v4, 0xffff0000, v4
	v_add_f32_e32 v2, v2, v3
	v_cndmask_b32_e32 v2, v34, v2, vcc
	v_cndmask_b32_e64 v5, v10, -v10, s[0:1]
	v_mov_b32_e32 v18, v15
	v_mul_f32_e32 v13, 0x3e38aa3b, v2
	v_pk_mul_f32 v[2:3], v[18:19], v[4:5]
	v_cvt_pk_bf16_f32 v110, v8, v6
	v_add_f32_e32 v2, v2, v3
	v_cndmask_b32_e32 v2, v4, v2, vcc
	v_mul_f32_e32 v4, 0x3e38aa3b, v2
	v_mov_b32_e32 v2, v16
	v_mov_b32_e32 v3, v20
	v_pk_mul_f32 v[2:3], v[2:3], v[36:37]
	v_mov_b32_e32 v20, v17
	v_add_f32_e32 v2, v2, v3
	v_cndmask_b32_e32 v2, v36, v2, vcc
	v_mul_f32_e32 v5, 0x3e38aa3b, v2
	v_pk_mul_f32 v[2:3], v[20:21], v[38:39]
	v_mov_b32_e32 v6, s73
	v_add_f32_e32 v2, v2, v3
	v_cndmask_b32_e32 v2, v38, v2, vcc
	v_mul_f32_e32 v2, 0x3e38aa3b, v2
	v_cvt_pk_bf16_f32 v113, v5, v2
	v_cvt_pk_bf16_f32 v112, v13, v4
	v_cvt_pk_bf16_f32 v111, v7, v9
	v_lshlrev_b32_e64 v225, v12, 1
	v_or_b32_e32 v227, 4, v211
	s_lshr_b32 s0, s3, 1
	s_add_i32 s0, s0, -1
	s_add_i32 s1, s73, 0x400
	v_mov_b32_e32 v6, 0x8000
	v_mov_b32_e32 v14, v224
	v_min_u32_e32 v2, s0, v14
	v_lshl_add_u32 v2, v2, 2, s73
	ds_read_b32 v16, v2
	v_add_u32_e32 v15, 64, v224
	v_min_u32_e32 v3, s0, v15
	v_lshl_add_u32 v3, v3, 2, s73
	ds_read_b32 v17, v3
	s_waitcnt lgkmcnt(0)
; #define LAS __attribute__((address_space(3)))
; #define F16_LOAD(S, KF, VF, E) do { const int sn_ = ((S) < nsteps) ? (S) : nsteps - 1; E = flash16_entry(sn_, list); const size_t go_ = (size_t)(E & 0xffffu) * 256; \
;         flash16_load(kb + go_, vb + go_, KF, VF); } while (0)
; __device__ __forceinline__ unsigned flash16_entry(int s, const LAS unsigned* list) {
;     const unsigned e = (unsigned)__builtin_amdgcn_readfirstlane((int)list[s >> 1]);
;     return (e & 0xffff0000u) | (2u * (e & 0xffffu) + (unsigned)(s & 1));
; }
; __device__ __forceinline__ void flash16_run(const bf16x8* kb, const bf16x8* vb, const bf16x8 (&qa)[2], const bf16x8 (&qb)[2], int nsteps, const LAS unsigned* list, int tq, int t0, int qi4, int fq, ...
;     if (nsteps <= 0) return;
;     bf16x8 kA[4], vA[4], kB[4], vB[4], kC[4], vC[4]; unsigned eA, eB, eC;
;     ...
;     F16_LOAD(0, kA, vA, eA); F16_LOAD(1, kB, vB, eB);
; __device__ __forceinline__ void nsa_tile(const Ctx& C, int b, int g, int t0) {
;     ...
;         float ma = -1e30f, la = 0.f, mb = -1e30f, lb = 0.f; f32x4v Oa[4], Ob[4];
; #pragma unroll
;         for (int dt = 0; dt < 4; ++dt) { Oa[dt] = (f32x4v){0.f, 0.f, 0.f, 0.f}; Ob[dt] = (f32x4v){0.f, 0.f, 0.f, 0.f}; }
;         flash16_run(kb, vb, q16f[0], q16f[1], 2 * nblk, list, tq, t0, qi4, fq, ma, la, Oa, mb, lb, Ob);
	v_and_b32_e32 v2, 0xffff, v16
	v_lshlrev_b32_e32 v2, 1, v2
	v_and_b32_e32 v3, 0xffff0000, v16
	v_or_b32_e32 v3, v3, v2
	v_lshl_add_u32 v4, v2, 5, 31
	v_cmp_ge_u32_e32 vcc, s97, v4
	v_add_u32_e32 v4, 32, v4
	v_lshl_add_u32 v7, v14, 3, s1
	v_cndmask_b32_e32 v5, 0, v6, vcc
	v_cmp_ge_u32_e32 vcc, s97, v4
	v_or_b32_e32 v8, v3, v5
	s_nop 0
	v_cndmask_b32_e32 v5, 0, v6, vcc
	v_or3_b32 v9, v3, v5, 1
	ds_write_b64 v7, v[8:9]
	v_and_b32_e32 v2, 0xffff, v17
	v_lshlrev_b32_e32 v2, 1, v2
	v_and_b32_e32 v3, 0xffff0000, v17
	v_or_b32_e32 v3, v3, v2
	v_lshl_add_u32 v4, v2, 5, 31
	v_cmp_ge_u32_e32 vcc, s97, v4
	v_add_u32_e32 v4, 32, v4
	v_lshl_add_u32 v7, v15, 3, s1
	v_cndmask_b32_e32 v5, 0, v6, vcc
	v_cmp_ge_u32_e32 vcc, s97, v4
	v_or_b32_e32 v8, v3, v5
	s_nop 0
	v_cndmask_b32_e32 v5, 0, v6, vcc
	v_or3_b32 v9, v3, v5, 1
	ds_write_b64 v7, v[8:9]
	v_mov_b32_e32 v18, v1
	v_mov_b32_e32 v19, v1
	v_mov_b32_e32 v20, v1
	v_mov_b32_e32 v21, v1
	v_mov_b32_e32 v22, v1
	v_mov_b32_e32 v23, v1
	v_mov_b32_e32 v24, v1
	v_mov_b32_e32 v25, v1
	v_mov_b32_e32 v26, v1
	v_mov_b32_e32 v27, v1
	v_mov_b32_e32 v28, v1
	v_mov_b32_e32 v29, v1
	v_mov_b32_e32 v30, v1
	v_mov_b32_e32 v31, v1
	v_mov_b32_e32 v32, v1
	v_mov_b32_e32 v33, v1
	v_mov_b32_e32 v34, v1
	v_mov_b32_e32 v35, v1
	v_mov_b32_e32 v36, v1
	v_mov_b32_e32 v37, v1
	v_mov_b32_e32 v38, v1
	v_mov_b32_e32 v39, v1
	v_mov_b32_e32 v40, v1
	v_mov_b32_e32 v41, v1
	v_mov_b32_e32 v42, v1
	v_mov_b32_e32 v43, v1
	v_mov_b32_e32 v44, v1
	v_mov_b32_e32 v45, v1
	v_mov_b32_e32 v46, v1
	v_mov_b32_e32 v47, v1
	v_mov_b32_e32 v48, v1
	v_mov_b32_e32 v49, v1
	v_mov_b32_e32 v236, v249
	v_mov_b32_e32 v237, v249
	v_mov_b32_e32 v94, v249
	v_mov_b32_e32 v95, v249
	v_mov_b32_e32 v96, 0x41000000
	v_mov_b32_e32 v240, 0
	v_mov_b32_e32 v241, 0
	v_mov_b32_e32 v238, 0
	v_mov_b32_e32 v239, 0
	v_mov_b32_e32 v55, s1
	s_waitcnt lgkmcnt(0)
	ds_read_b32 v14, v55
	ds_read_b32 v15, v55 offset:4
	ds_read_b32 v16, v55 offset:8
	ds_read_b32 v54, v55 offset:12
	v_add_u32_e32 v55, 16, v55
	s_waitcnt lgkmcnt(0)
	v_readfirstlane_b32 s16, v14
	v_readfirstlane_b32 s17, v15
	v_readfirstlane_b32 s19, v16
	s_and_b32 s6, s16, 0x7fff
	s_lshl_b32 s6, s6, 12
	v_lshl_add_u64 v[56:57], v[230:231], 0, s[6:7]
	v_lshl_add_u64 v[58:59], v[234:235], 0, s[6:7]
	global_load_dwordx4 v[114:117], v[56:57], off
	global_load_dwordx4 v[118:121], v[56:57], off offset:1024
	global_load_dwordx4 v[122:125], v[56:57], off offset:2048
	global_load_dwordx4 v[126:129], v[56:57], off offset:3072
	global_load_dwordx4 v[130:133], v[58:59], off
	global_load_dwordx4 v[134:137], v[58:59], off offset:1024
	global_load_dwordx4 v[138:141], v[58:59], off offset:2048
	global_load_dwordx4 v[142:145], v[58:59], off offset:3072
	s_and_b32 s6, s17, 0x7fff
	s_lshl_b32 s6, s6, 12
	v_lshl_add_u64 v[56:57], v[230:231], 0, s[6:7]
	v_lshl_add_u64 v[58:59], v[234:235], 0, s[6:7]
	global_load_dwordx4 v[146:149], v[56:57], off
	global_load_dwordx4 v[150:153], v[56:57], off offset:1024
	global_load_dwordx4 v[154:157], v[56:57], off offset:2048
	global_load_dwordx4 v[158:161], v[56:57], off offset:3072
	global_load_dwordx4 v[162:165], v[58:59], off
	global_load_dwordx4 v[166:169], v[58:59], off offset:1024
	global_load_dwordx4 v[170:173], v[58:59], off offset:2048
	global_load_dwordx4 v[174:177], v[58:59], off offset:3072
	s_and_b32 s6, s19, 0x7fff
	s_lshl_b32 s6, s6, 12
	v_lshl_add_u64 v[56:57], v[230:231], 0, s[6:7]
	v_lshl_add_u64 v[58:59], v[234:235], 0, s[6:7]
	global_load_dwordx4 v[178:181], v[56:57], off
	global_load_dwordx4 v[182:185], v[56:57], off offset:1024
	global_load_dwordx4 v[186:189], v[56:57], off offset:2048
	global_load_dwordx4 v[190:193], v[56:57], off offset:3072
	global_load_dwordx4 v[194:197], v[58:59], off
	global_load_dwordx4 v[198:201], v[58:59], off offset:1024
	global_load_dwordx4 v[202:205], v[58:59], off offset:2048
	global_load_dwordx4 v[206:209], v[58:59], off offset:3072
	s_mov_b32 s2, 0

; __device__ __forceinline__ f32x4v mfma16(bf16x8 a, bf16x8 b, f32x4v c) { return __builtin_amdgcn_mfma_f32_16x16x32_bf16(a, b, c, 0, 0, 0); }
; __device__ __forceinline__ void flash16_compute(bool domask, const bf16x8 (&kf)[4], const bf16x8 (&vf)[4], const bf16x8 (&q)[2], int x0, unsigned span, float& m, float& l, f32x4v (&O)[4]) {
;     f32x4v s0 = {0.f, 0.f, 0.f, 0.f}, s1 = {0.f, 0.f, 0.f, 0.f};
;     __builtin_amdgcn_s_setprio(1);
;     s0 = mfma16(kf[0], q[0], s0); s1 = mfma16(kf[2], q[0], s1);
;     s0 = mfma16(kf[1], q[1], s0); s1 = mfma16(kf[3], q[1], s1);
;     __builtin_amdgcn_s_setprio(0);
;     float sc[8] = {s0[0], s0[1], s0[2], s0[3], s1[0], s1[1], s1[2], s1[3]};
;     if (domask) {
; #pragma unroll
;         for (int j = 0; j < 8; ++j) sc[j] = ((unsigned)(x0 + j) <= span) ? sc[j] : -1e30f;
;     }
.Lsel_slow_Aa:
	s_and_b32 s5, s16, 0x7fff
	s_lshl_b32 s5, s5, 5
	v_subrev_u32_e32 v16, s5, v211
	s_nop 0
	v_cndmask_b32_e64 v16, v16, -1, vcc
	v_cmp_lt_i32_e32 vcc, -1, v16
	v_max_i32_e32 v17, 0, v16
	s_nop 0
	v_cndmask_b32_e32 v16, 64, v232, vcc
	v_cmp_le_u32_e32 vcc, v16, v17
	s_nop 1
	v_cndmask_b32_e32 v2, v249, v240, vcc
	v_or_b32_e32 v15, 1, v16
	v_cmp_le_u32_e32 vcc, v15, v17
	s_nop 1
	v_cndmask_b32_e32 v3, v249, v240, vcc
	v_or_b32_e32 v15, 2, v16
	v_cmp_le_u32_e32 vcc, v15, v17
	s_nop 1
	v_cndmask_b32_e32 v4, v249, v240, vcc
	v_or_b32_e32 v15, 3, v16
	v_cmp_le_u32_e32 vcc, v15, v17
	s_nop 1
	v_cndmask_b32_e32 v5, v249, v240, vcc
	v_or_b32_e32 v15, 4, v16
	v_cmp_le_u32_e32 vcc, v15, v17
	s_nop 1
	v_cndmask_b32_e32 v6, v249, v240, vcc
	v_or_b32_e32 v15, 5, v16
	v_cmp_le_u32_e32 vcc, v15, v17
	s_nop 1
	v_cndmask_b32_e32 v7, v249, v240, vcc
	v_or_b32_e32 v15, 6, v16
	v_cmp_le_u32_e32 vcc, v15, v17
	s_nop 1
	v_cndmask_b32_e32 v8, v249, v240, vcc
	v_or_b32_e32 v15, 7, v16
	v_cmp_le_u32_e32 vcc, v15, v17
	s_nop 1
	v_cndmask_b32_e32 v9, v249, v240, vcc
	s_nop 1
	v_mfma_f32_16x16x32_bf16 v[2:5], v[114:117], v[102:105], v[2:5]
	v_mfma_f32_16x16x32_bf16 v[6:9], v[122:125], v[102:105], v[6:9]
	s_branch .Lsel_qk2_Aa

; __device__ __forceinline__ f32x4v mfma16(bf16x8 a, bf16x8 b, f32x4v c) { return __builtin_amdgcn_mfma_f32_16x16x32_bf16(a, b, c, 0, 0, 0); }
; __device__ __forceinline__ void flash16_compute(bool domask, const bf16x8 (&kf)[4], const bf16x8 (&vf)[4], const bf16x8 (&q)[2], int x0, unsigned span, float& m, float& l, f32x4v (&O)[4]) {
;     f32x4v s0 = {0.f, 0.f, 0.f, 0.f}, s1 = {0.f, 0.f, 0.f, 0.f};
;     __builtin_amdgcn_s_setprio(1);
;     s0 = mfma16(kf[0], q[0], s0); s1 = mfma16(kf[2], q[0], s1);
;     s0 = mfma16(kf[1], q[1], s0); s1 = mfma16(kf[3], q[1], s1);
;     __builtin_amdgcn_s_setprio(0);
;     float sc[8] = {s0[0], s0[1], s0[2], s0[3], s1[0], s1[1], s1[2], s1[3]};
;     if (domask) {
; #pragma unroll
;         for (int j = 0; j < 8; ++j) sc[j] = ((unsigned)(x0 + j) <= span) ? sc[j] : -1e30f;
;     }
.Lsel_slow_Ab:
	s_and_b32 s5, s16, 0x7fff
	s_lshl_b32 s5, s5, 5
	v_subrev_u32_e32 v16, s5, v227
	s_nop 0
	v_cndmask_b32_e64 v16, v16, -1, vcc
	v_cmp_lt_i32_e32 vcc, -1, v16
	v_max_i32_e32 v17, 0, v16
	s_nop 0
	v_cndmask_b32_e32 v16, 64, v232, vcc
	v_cmp_le_u32_e32 vcc, v16, v17
	s_nop 1
	v_cndmask_b32_e32 v2, v249, v241, vcc
	v_or_b32_e32 v15, 1, v16
	v_cmp_le_u32_e32 vcc, v15, v17
	s_nop 1
	v_cndmask_b32_e32 v3, v249, v241, vcc
	v_or_b32_e32 v15, 2, v16
	v_cmp_le_u32_e32 vcc, v15, v17
	s_nop 1
	v_cndmask_b32_e32 v4, v249, v241, vcc
	v_or_b32_e32 v15, 3, v16
	v_cmp_le_u32_e32 vcc, v15, v17
	s_nop 1
	v_cndmask_b32_e32 v5, v249, v241, vcc
	v_or_b32_e32 v15, 4, v16
	v_cmp_le_u32_e32 vcc, v15, v17
	s_nop 1
	v_cndmask_b32_e32 v6, v249, v241, vcc
	v_or_b32_e32 v15, 5, v16
	v_cmp_le_u32_e32 vcc, v15, v17
	s_nop 1
	v_cndmask_b32_e32 v7, v249, v241, vcc
	v_or_b32_e32 v15, 6, v16
	v_cmp_le_u32_e32 vcc, v15, v17
	s_nop 1
	v_cndmask_b32_e32 v8, v249, v241, vcc
	v_or_b32_e32 v15, 7, v16
	v_cmp_le_u32_e32 vcc, v15, v17
	s_nop 1
	v_cndmask_b32_e32 v9, v249, v241, vcc
	s_nop 1
	v_mfma_f32_16x16x32_bf16 v[2:5], v[114:117], v[110:113], v[2:5]
	v_mfma_f32_16x16x32_bf16 v[6:9], v[122:125], v[110:113], v[6:9]
	s_branch .Lsel_qk2_Ab

; __device__ __forceinline__ f32x4v mfma16(bf16x8 a, bf16x8 b, f32x4v c) { return __builtin_amdgcn_mfma_f32_16x16x32_bf16(a, b, c, 0, 0, 0); }
; __device__ __forceinline__ void flash16_compute(bool domask, const bf16x8 (&kf)[4], const bf16x8 (&vf)[4], const bf16x8 (&q)[2], int x0, unsigned span, float& m, float& l, f32x4v (&O)[4]) {
;     f32x4v s0 = {0.f, 0.f, 0.f, 0.f}, s1 = {0.f, 0.f, 0.f, 0.f};
;     __builtin_amdgcn_s_setprio(1);
;     s0 = mfma16(kf[0], q[0], s0); s1 = mfma16(kf[2], q[0], s1);
;     s0 = mfma16(kf[1], q[1], s0); s1 = mfma16(kf[3], q[1], s1);
;     __builtin_amdgcn_s_setprio(0);
;     float sc[8] = {s0[0], s0[1], s0[2], s0[3], s1[0], s1[1], s1[2], s1[3]};
;     if (domask) {
; #pragma unroll
;         for (int j = 0; j < 8; ++j) sc[j] = ((unsigned)(x0 + j) <= span) ? sc[j] : -1e30f;
;     }
.Lsel_slow_Ba:
	s_and_b32 s5, s17, 0x7fff
	s_lshl_b32 s5, s5, 5
	v_subrev_u32_e32 v16, s5, v211
	s_nop 0
	v_cndmask_b32_e64 v16, v16, -1, vcc
	v_cmp_lt_i32_e32 vcc, -1, v16
	v_max_i32_e32 v17, 0, v16
	s_nop 0
	v_cndmask_b32_e32 v16, 64, v232, vcc
	v_cmp_le_u32_e32 vcc, v16, v17
	s_nop 1
	v_cndmask_b32_e32 v2, v249, v240, vcc
	v_or_b32_e32 v15, 1, v16
	v_cmp_le_u32_e32 vcc, v15, v17
	s_nop 1
	v_cndmask_b32_e32 v3, v249, v240, vcc
	v_or_b32_e32 v15, 2, v16
	v_cmp_le_u32_e32 vcc, v15, v17
	s_nop 1
	v_cndmask_b32_e32 v4, v249, v240, vcc
	v_or_b32_e32 v15, 3, v16
	v_cmp_le_u32_e32 vcc, v15, v17
	s_nop 1
	v_cndmask_b32_e32 v5, v249, v240, vcc
	v_or_b32_e32 v15, 4, v16
	v_cmp_le_u32_e32 vcc, v15, v17
	s_nop 1
	v_cndmask_b32_e32 v6, v249, v240, vcc
	v_or_b32_e32 v15, 5, v16
	v_cmp_le_u32_e32 vcc, v15, v17
	s_nop 1
	v_cndmask_b32_e32 v7, v249, v240, vcc
	v_or_b32_e32 v15, 6, v16
	v_cmp_le_u32_e32 vcc, v15, v17
	s_nop 1
	v_cndmask_b32_e32 v8, v249, v240, vcc
	v_or_b32_e32 v15, 7, v16
	v_cmp_le_u32_e32 vcc, v15, v17
	s_nop 1
	v_cndmask_b32_e32 v9, v249, v240, vcc
	s_nop 1
	v_mfma_f32_16x16x32_bf16 v[2:5], v[146:149], v[102:105], v[2:5]
	v_mfma_f32_16x16x32_bf16 v[6:9], v[154:157], v[102:105], v[6:9]
	s_branch .Lsel_qk2_Ba

; __device__ __forceinline__ f32x4v mfma16(bf16x8 a, bf16x8 b, f32x4v c) { return __builtin_amdgcn_mfma_f32_16x16x32_bf16(a, b, c, 0, 0, 0); }
; __device__ __forceinline__ void flash16_compute(bool domask, const bf16x8 (&kf)[4], const bf16x8 (&vf)[4], const bf16x8 (&q)[2], int x0, unsigned span, float& m, float& l, f32x4v (&O)[4]) {
;     f32x4v s0 = {0.f, 0.f, 0.f, 0.f}, s1 = {0.f, 0.f, 0.f, 0.f};
;     __builtin_amdgcn_s_setprio(1);
;     s0 = mfma16(kf[0], q[0], s0); s1 = mfma16(kf[2], q[0], s1);
;     s0 = mfma16(kf[1], q[1], s0); s1 = mfma16(kf[3], q[1], s1);
;     __builtin_amdgcn_s_setprio(0);
;     float sc[8] = {s0[0], s0[1], s0[2], s0[3], s1[0], s1[1], s1[2], s1[3]};
;     if (domask) {
; #pragma unroll
;         for (int j = 0; j < 8; ++j) sc[j] = ((unsigned)(x0 + j) <= span) ? sc[j] : -1e30f;
;     }
.Lsel_slow_Bb:
	s_and_b32 s5, s17, 0x7fff
	s_lshl_b32 s5, s5, 5
	v_subrev_u32_e32 v16, s5, v227
	s_nop 0
	v_cndmask_b32_e64 v16, v16, -1, vcc
	v_cmp_lt_i32_e32 vcc, -1, v16
	v_max_i32_e32 v17, 0, v16
	s_nop 0
	v_cndmask_b32_e32 v16, 64, v232, vcc
	v_cmp_le_u32_e32 vcc, v16, v17
	s_nop 1
	v_cndmask_b32_e32 v2, v249, v241, vcc
	v_or_b32_e32 v15, 1, v16
	v_cmp_le_u32_e32 vcc, v15, v17
	s_nop 1
	v_cndmask_b32_e32 v3, v249, v241, vcc
	v_or_b32_e32 v15, 2, v16
	v_cmp_le_u32_e32 vcc, v15, v17
	s_nop 1
	v_cndmask_b32_e32 v4, v249, v241, vcc
	v_or_b32_e32 v15, 3, v16
	v_cmp_le_u32_e32 vcc, v15, v17
	s_nop 1
	v_cndmask_b32_e32 v5, v249, v241, vcc
	v_or_b32_e32 v15, 4, v16
	v_cmp_le_u32_e32 vcc, v15, v17
	s_nop 1
	v_cndmask_b32_e32 v6, v249, v241, vcc
	v_or_b32_e32 v15, 5, v16
	v_cmp_le_u32_e32 vcc, v15, v17
	s_nop 1
	v_cndmask_b32_e32 v7, v249, v241, vcc
	v_or_b32_e32 v15, 6, v16
	v_cmp_le_u32_e32 vcc, v15, v17
	s_nop 1
	v_cndmask_b32_e32 v8, v249, v241, vcc
	v_or_b32_e32 v15, 7, v16
	v_cmp_le_u32_e32 vcc, v15, v17
	s_nop 1
	v_cndmask_b32_e32 v9, v249, v241, vcc
	s_nop 1
	v_mfma_f32_16x16x32_bf16 v[2:5], v[146:149], v[110:113], v[2:5]
	v_mfma_f32_16x16x32_bf16 v[6:9], v[154:157], v[110:113], v[6:9]
	s_branch .Lsel_qk2_Bb

; __device__ __forceinline__ f32x4v mfma16(bf16x8 a, bf16x8 b, f32x4v c) { return __builtin_amdgcn_mfma_f32_16x16x32_bf16(a, b, c, 0, 0, 0); }
; __device__ __forceinline__ void flash16_compute(bool domask, const bf16x8 (&kf)[4], const bf16x8 (&vf)[4], const bf16x8 (&q)[2], int x0, unsigned span, float& m, float& l, f32x4v (&O)[4]) {
;     f32x4v s0 = {0.f, 0.f, 0.f, 0.f}, s1 = {0.f, 0.f, 0.f, 0.f};
;     __builtin_amdgcn_s_setprio(1);
;     s0 = mfma16(kf[0], q[0], s0); s1 = mfma16(kf[2], q[0], s1);
;     s0 = mfma16(kf[1], q[1], s0); s1 = mfma16(kf[3], q[1], s1);
;     __builtin_amdgcn_s_setprio(0);
;     float sc[8] = {s0[0], s0[1], s0[2], s0[3], s1[0], s1[1], s1[2], s1[3]};
;     if (domask) {
; #pragma unroll
;         for (int j = 0; j < 8; ++j) sc[j] = ((unsigned)(x0 + j) <= span) ? sc[j] : -1e30f;
;     }
.Lsel_slow_Ca:
	s_and_b32 s5, s19, 0x7fff
	s_lshl_b32 s5, s5, 5
	v_subrev_u32_e32 v16, s5, v211
	s_nop 0
	v_cndmask_b32_e64 v16, v16, -1, vcc
	v_cmp_lt_i32_e32 vcc, -1, v16
	v_max_i32_e32 v17, 0, v16
	s_nop 0
	v_cndmask_b32_e32 v16, 64, v232, vcc
	v_cmp_le_u32_e32 vcc, v16, v17
	s_nop 1
	v_cndmask_b32_e32 v2, v249, v240, vcc
	v_or_b32_e32 v15, 1, v16
	v_cmp_le_u32_e32 vcc, v15, v17
	s_nop 1
	v_cndmask_b32_e32 v3, v249, v240, vcc
	v_or_b32_e32 v15, 2, v16
	v_cmp_le_u32_e32 vcc, v15, v17
	s_nop 1
	v_cndmask_b32_e32 v4, v249, v240, vcc
	v_or_b32_e32 v15, 3, v16
	v_cmp_le_u32_e32 vcc, v15, v17
	s_nop 1
	v_cndmask_b32_e32 v5, v249, v240, vcc
	v_or_b32_e32 v15, 4, v16
	v_cmp_le_u32_e32 vcc, v15, v17
	s_nop 1
	v_cndmask_b32_e32 v6, v249, v240, vcc
	v_or_b32_e32 v15, 5, v16
	v_cmp_le_u32_e32 vcc, v15, v17
	s_nop 1
	v_cndmask_b32_e32 v7, v249, v240, vcc
	v_or_b32_e32 v15, 6, v16
	v_cmp_le_u32_e32 vcc, v15, v17
	s_nop 1
	v_cndmask_b32_e32 v8, v249, v240, vcc
	v_or_b32_e32 v15, 7, v16
	v_cmp_le_u32_e32 vcc, v15, v17
	s_nop 1
	v_cndmask_b32_e32 v9, v249, v240, vcc
	s_nop 1
	v_mfma_f32_16x16x32_bf16 v[2:5], v[178:181], v[102:105], v[2:5]
	v_mfma_f32_16x16x32_bf16 v[6:9], v[186:189], v[102:105], v[6:9]
	s_branch .Lsel_qk2_Ca

; __device__ __forceinline__ f32x4v mfma16(bf16x8 a, bf16x8 b, f32x4v c) { return __builtin_amdgcn_mfma_f32_16x16x32_bf16(a, b, c, 0, 0, 0); }
; __device__ __forceinline__ void flash16_compute(bool domask, const bf16x8 (&kf)[4], const bf16x8 (&vf)[4], const bf16x8 (&q)[2], int x0, unsigned span, float& m, float& l, f32x4v (&O)[4]) {
;     f32x4v s0 = {0.f, 0.f, 0.f, 0.f}, s1 = {0.f, 0.f, 0.f, 0.f};
;     __builtin_amdgcn_s_setprio(1);
;     s0 = mfma16(kf[0], q[0], s0); s1 = mfma16(kf[2], q[0], s1);
;     s0 = mfma16(kf[1], q[1], s0); s1 = mfma16(kf[3], q[1], s1);
;     __builtin_amdgcn_s_setprio(0);
;     float sc[8] = {s0[0], s0[1], s0[2], s0[3], s1[0], s1[1], s1[2], s1[3]};
;     if (domask) {
; #pragma unroll
;         for (int j = 0; j < 8; ++j) sc[j] = ((unsigned)(x0 + j) <= span) ? sc[j] : -1e30f;
;     }
.Lsel_slow_Cb:
	s_and_b32 s5, s19, 0x7fff
	s_lshl_b32 s5, s5, 5
	v_subrev_u32_e32 v16, s5, v227
	s_nop 0
	v_cndmask_b32_e64 v16, v16, -1, vcc
	v_cmp_lt_i32_e32 vcc, -1, v16
	v_max_i32_e32 v17, 0, v16
	s_nop 0
	v_cndmask_b32_e32 v16, 64, v232, vcc
	v_cmp_le_u32_e32 vcc, v16, v17
	s_nop 1
	v_cndmask_b32_e32 v2, v249, v241, vcc
	v_or_b32_e32 v15, 1, v16
	v_cmp_le_u32_e32 vcc, v15, v17
	s_nop 1
	v_cndmask_b32_e32 v3, v249, v241, vcc
	v_or_b32_e32 v15, 2, v16
	v_cmp_le_u32_e32 vcc, v15, v17
	s_nop 1
	v_cndmask_b32_e32 v4, v249, v241, vcc
	v_or_b32_e32 v15, 3, v16
	v_cmp_le_u32_e32 vcc, v15, v17
	s_nop 1
	v_cndmask_b32_e32 v5, v249, v241, vcc
	v_or_b32_e32 v15, 4, v16
	v_cmp_le_u32_e32 vcc, v15, v17
	s_nop 1
	v_cndmask_b32_e32 v6, v249, v241, vcc
	v_or_b32_e32 v15, 5, v16
	v_cmp_le_u32_e32 vcc, v15, v17
	s_nop 1
	v_cndmask_b32_e32 v7, v249, v241, vcc
	v_or_b32_e32 v15, 6, v16
	v_cmp_le_u32_e32 vcc, v15, v17
	s_nop 1
	v_cndmask_b32_e32 v8, v249, v241, vcc
	v_or_b32_e32 v15, 7, v16
	v_cmp_le_u32_e32 vcc, v15, v17
	s_nop 1
	v_cndmask_b32_e32 v9, v249, v241, vcc
	s_nop 1
	v_mfma_f32_16x16x32_bf16 v[2:5], v[178:181], v[110:113], v[2:5]
	v_mfma_f32_16x16x32_bf16 v[6:9], v[186:189], v[110:113], v[6:9]
	s_branch .Lsel_qk2_Cb

; __device__ __forceinline__ f32x4v mfma16(bf16x8 a, bf16x8 b, f32x4v c) { return __builtin_amdgcn_mfma_f32_16x16x32_bf16(a, b, c, 0, 0, 0); }
; __device__ __forceinline__ void flash16_compute(bool domask, const bf16x8 (&kf)[4], const bf16x8 (&vf)[4], const bf16x8 (&q)[2], int x0, unsigned span, float& m, float& l, f32x4v (&O)[4]) {
;     f32x4v s0 = {0.f, 0.f, 0.f, 0.f}, s1 = {0.f, 0.f, 0.f, 0.f};
;     __builtin_amdgcn_s_setprio(1);
;     s0 = mfma16(kf[0], q[0], s0); s1 = mfma16(kf[2], q[0], s1);
;     s0 = mfma16(kf[1], q[1], s0); s1 = mfma16(kf[3], q[1], s1);
;     __builtin_amdgcn_s_setprio(0);
;     float sc[8] = {s0[0], s0[1], s0[2], s0[3], s1[0], s1[1], s1[2], s1[3]};
;     if (domask) {
; #pragma unroll
;         for (int j = 0; j < 8; ++j) sc[j] = ((unsigned)(x0 + j) <= span) ? sc[j] : -1e30f;
;     }
.Lsel_slow_Da:
	s_and_b32 s5, s4, 0x7fff
	s_lshl_b32 s5, s5, 5
	v_subrev_u32_e32 v16, s5, v211
	s_nop 0
	v_cndmask_b32_e64 v16, v16, -1, vcc
	v_cmp_lt_i32_e32 vcc, -1, v16
	v_max_i32_e32 v17, 0, v16
	s_nop 0
	v_cndmask_b32_e32 v16, 64, v232, vcc
	v_cmp_le_u32_e32 vcc, v16, v17
	s_nop 1
	v_cndmask_b32_e32 v2, v249, v240, vcc
	v_or_b32_e32 v15, 1, v16
	v_cmp_le_u32_e32 vcc, v15, v17
	s_nop 1
	v_cndmask_b32_e32 v3, v249, v240, vcc
	v_or_b32_e32 v15, 2, v16
	v_cmp_le_u32_e32 vcc, v15, v17
	s_nop 1
	v_cndmask_b32_e32 v4, v249, v240, vcc
	v_or_b32_e32 v15, 3, v16
	v_cmp_le_u32_e32 vcc, v15, v17
	s_nop 1
	v_cndmask_b32_e32 v5, v249, v240, vcc
	v_or_b32_e32 v15, 4, v16
	v_cmp_le_u32_e32 vcc, v15, v17
	s_nop 1
	v_cndmask_b32_e32 v6, v249, v240, vcc
	v_or_b32_e32 v15, 5, v16
	v_cmp_le_u32_e32 vcc, v15, v17
	s_nop 1
	v_cndmask_b32_e32 v7, v249, v240, vcc
	v_or_b32_e32 v15, 6, v16
	v_cmp_le_u32_e32 vcc, v15, v17
	s_nop 1
	v_cndmask_b32_e32 v8, v249, v240, vcc
	v_or_b32_e32 v15, 7, v16
	v_cmp_le_u32_e32 vcc, v15, v17
	s_nop 1
	v_cndmask_b32_e32 v9, v249, v240, vcc
	s_nop 1
	v_mfma_f32_16x16x32_bf16 v[2:5], v[62:65], v[102:105], v[2:5]
	v_mfma_f32_16x16x32_bf16 v[6:9], v[70:73], v[102:105], v[6:9]
	s_branch .Lsel_qk2_Da

; __device__ __forceinline__ f32x4v mfma16(bf16x8 a, bf16x8 b, f32x4v c) { return __builtin_amdgcn_mfma_f32_16x16x32_bf16(a, b, c, 0, 0, 0); }
; __device__ __forceinline__ void flash16_compute(bool domask, const bf16x8 (&kf)[4], const bf16x8 (&vf)[4], const bf16x8 (&q)[2], int x0, unsigned span, float& m, float& l, f32x4v (&O)[4]) {
;     f32x4v s0 = {0.f, 0.f, 0.f, 0.f}, s1 = {0.f, 0.f, 0.f, 0.f};
;     __builtin_amdgcn_s_setprio(1);
;     s0 = mfma16(kf[0], q[0], s0); s1 = mfma16(kf[2], q[0], s1);
;     s0 = mfma16(kf[1], q[1], s0); s1 = mfma16(kf[3], q[1], s1);
;     __builtin_amdgcn_s_setprio(0);
;     float sc[8] = {s0[0], s0[1], s0[2], s0[3], s1[0], s1[1], s1[2], s1[3]};
;     if (domask) {
; #pragma unroll
;         for (int j = 0; j < 8; ++j) sc[j] = ((unsigned)(x0 + j) <= span) ? sc[j] : -1e30f;
;     }
.Lsel_slow_Db:
	s_and_b32 s5, s4, 0x7fff
	s_lshl_b32 s5, s5, 5
	v_subrev_u32_e32 v16, s5, v227
	s_nop 0
	v_cndmask_b32_e64 v16, v16, -1, vcc
	v_cmp_lt_i32_e32 vcc, -1, v16
	v_max_i32_e32 v17, 0, v16
	s_nop 0
	v_cndmask_b32_e32 v16, 64, v232, vcc
	v_cmp_le_u32_e32 vcc, v16, v17
	s_nop 1
	v_cndmask_b32_e32 v2, v249, v241, vcc
	v_or_b32_e32 v15, 1, v16
	v_cmp_le_u32_e32 vcc, v15, v17
	s_nop 1
	v_cndmask_b32_e32 v3, v249, v241, vcc
	v_or_b32_e32 v15, 2, v16
	v_cmp_le_u32_e32 vcc, v15, v17
	s_nop 1
	v_cndmask_b32_e32 v4, v249, v241, vcc
	v_or_b32_e32 v15, 3, v16
	v_cmp_le_u32_e32 vcc, v15, v17
	s_nop 1
	v_cndmask_b32_e32 v5, v249, v241, vcc
	v_or_b32_e32 v15, 4, v16
	v_cmp_le_u32_e32 vcc, v15, v17
	s_nop 1
	v_cndmask_b32_e32 v6, v249, v241, vcc
	v_or_b32_e32 v15, 5, v16
	v_cmp_le_u32_e32 vcc, v15, v17
	s_nop 1
	v_cndmask_b32_e32 v7, v249, v241, vcc
	v_or_b32_e32 v15, 6, v16
	v_cmp_le_u32_e32 vcc, v15, v17
	s_nop 1
	v_cndmask_b32_e32 v8, v249, v241, vcc
	v_or_b32_e32 v15, 7, v16
	v_cmp_le_u32_e32 vcc, v15, v17
	s_nop 1
	v_cndmask_b32_e32 v9, v249, v241, vcc
	s_nop 1
	v_mfma_f32_16x16x32_bf16 v[2:5], v[62:65], v[110:113], v[2:5]
	v_mfma_f32_16x16x32_bf16 v[6:9], v[70:73], v[110:113], v[6:9]
	s_branch .Lsel_qk2_Db
